# SSD first-half staging: final load wait leaves the previous step's two write-through y stores in flight (vmcnt(2)); on top of v52
# baseline (speedup 1.0000x reference)
.Lmy_w0_a:
	s_cmp_lt_u32 s47, 3
	s_cbranch_scc1 .Lmy_w00_a
	s_waitcnt vmcnt(2)
	s_branch .Lmy_w1_a

.Lmy_w0_b:
	s_cmp_lt_u32 s34, 3
	s_cbranch_scc1 .Lmy_w00_b
	s_waitcnt vmcnt(2)
	s_branch .Lmy_w1_b
